# R1S chunk scans as a compact loop (2 register sets, both directions through one code path) instead of unrolled
# baseline (speedup 1.0000x reference)
; __device__ __forceinline__ float log2_gamma(float logit) { return -log1pf(expf(-logit)) * 1.4426950408889634f; }
; __device__ __forceinline__ void r1s_phase(KP p, int G, int bid, int wv) {
;     ...
;     for (int u = bid; u < 256; u += G) {
;         const int bh = u >> 3, s = u & 7, h = bh & 7;
;         float lf = log2_gamma(p->in[18][h]), lb = log2_gamma(p->in[19][h]);
;         asm volatile("" : "+v"(lf), "+v"(lb));
.LBB0_113:
	s_ashr_i32 s10, s1, 3
	s_lshl_b32 s8, s10, 2
	s_and_b32 s8, s8, 28
	v_mov_b32_e32 v18, s8
	s_waitcnt lgkmcnt(0)
	global_load_dword v2, v18, s[4:5]
	v_mov_b32_e32 v219, v246
	s_lshl_b32 s16, s10, 1
	s_ashr_i32 s17, s16, 31
	s_mul_i32 s18, s10, 18
	s_lshl_b64 s[8:9], s[16:17], 19
	s_and_b32 s11, s0, 0x70
	s_ashr_i32 s19, s18, 31
	s_lshl_b32 s46, s11, 1
	v_mov_b32_e32 v83, v1
	s_waitcnt vmcnt(0)
	v_mul_f32_e32 v3, 0xbfb8aa3b, v2
	v_fma_f32 v4, v2, s12, -v3
	v_rndne_f32_e32 v5, v3
	v_fmac_f32_e32 v4, 0xb2a5705f, v2
	v_sub_f32_e32 v3, v3, v5
	v_add_f32_e32 v3, v3, v4
	v_exp_f32_e32 v3, v3
	v_cvt_i32_f32_e32 v4, v5
	v_cmp_nlt_f32_e32 vcc, s93, v2
	v_ldexp_f32 v3, v3, v4
	s_nop 0
	v_cndmask_b32_e32 v3, 0, v3, vcc
	v_cmp_ngt_f32_e32 vcc, s13, v2
	s_nop 1
	v_cndmask_b32_e32 v19, v222, v3, vcc
	v_add_f32_e32 v4, 1.0, v19
	v_add_f32_e32 v2, -1.0, v4
	v_sub_f32_e32 v3, v2, v4
	v_add_f32_e32 v3, 1.0, v3
	v_sub_f32_e32 v2, v19, v2
	v_add_f32_e32 v5, v2, v3
	v_frexp_mant_f32_e32 v2, v4
	v_cmp_gt_f32_e32 vcc, s35, v2
	v_cvt_f64_f32_e32 v[2:3], v4
	v_frexp_exp_i32_f64_e32 v2, v[2:3]
	v_subbrev_co_u32_e32 v10, vcc, 0, v2, vcc
	v_sub_u32_e32 v2, 0, v10
	v_ldexp_f32 v3, v4, v2
	v_add_f32_e32 v4, -1.0, v3
	v_add_f32_e32 v6, 1.0, v3
	v_ldexp_f32 v2, v5, v2
	v_add_f32_e32 v5, 1.0, v4
	v_add_f32_e32 v7, -1.0, v6
	v_sub_f32_e32 v5, v3, v5
	v_sub_f32_e32 v3, v3, v7
	v_add_f32_e32 v5, v2, v5
	v_add_f32_e32 v2, v2, v3
	v_add_f32_e32 v11, v6, v2
	v_rcp_f32_e32 v13, v11
	v_sub_f32_e32 v3, v6, v11
	v_add_f32_e32 v12, v2, v3
	v_add_f32_e32 v3, v4, v5
	v_mul_f32_e32 v15, v3, v13
	v_sub_f32_e32 v2, v4, v3
	v_mul_f32_e32 v4, v11, v15
	v_fma_f32 v6, v15, v11, -v4
	v_fmac_f32_e32 v6, v15, v12
	v_add_f32_e32 v14, v5, v2
	v_add_f32_e32 v2, v4, v6
	v_sub_f32_e32 v5, v3, v2
	v_pk_add_f32 v[8:9], v[2:3], v[4:5] neg_lo:[0,1] neg_hi:[0,1]
	v_mov_b32_e32 v7, v2
	v_pk_add_f32 v[2:3], v[8:9], v[6:7] neg_lo:[0,1] neg_hi:[0,1]
	v_cmp_neq_f32_e32 vcc, s14, v19
	v_add_f32_e32 v3, v14, v3
	v_add_f32_e32 v2, v2, v3
	v_add_f32_e32 v3, v5, v2
	v_mul_f32_e32 v14, v13, v3
	v_mul_f32_e32 v4, v11, v14
	v_fma_f32 v6, v14, v11, -v4
	v_fmac_f32_e32 v6, v14, v12
	v_sub_f32_e32 v5, v5, v3
	v_add_f32_e32 v11, v2, v5
	v_add_f32_e32 v2, v4, v6
	v_sub_f32_e32 v5, v3, v2
	v_pk_add_f32 v[8:9], v[2:3], v[4:5] neg_lo:[0,1] neg_hi:[0,1]
	v_mov_b32_e32 v7, v2
	v_pk_add_f32 v[2:3], v[8:9], v[6:7] neg_lo:[0,1] neg_hi:[0,1]
	s_nop 0
	v_add_f32_e32 v3, v11, v3
	v_add_f32_e32 v2, v2, v3
	v_add_f32_e32 v3, v15, v14
	v_add_f32_e32 v2, v5, v2
	v_sub_f32_e32 v4, v3, v15
	v_mul_f32_e32 v2, v13, v2
	v_sub_f32_e32 v4, v14, v4
	v_add_f32_e32 v4, v4, v2
	v_add_f32_e32 v6, v3, v4
	v_mul_f32_e32 v7, v6, v6
	v_fmamk_f32 v2, v7, 0x3e9b6dac, v246
	v_fmaak_f32 v163, v7, v2, 0x3f2aaada
	v_cvt_f32_i32_e32 v2, v10
	v_sub_f32_e32 v3, v6, v3
	v_sub_f32_e32 v3, v4, v3
	v_ldexp_f32 v8, v3, 1
	v_mul_f32_e32 v3, v6, v7
	v_ldexp_f32 v5, v6, 1
	v_pk_mul_f32 v[6:7], v[2:3], v[162:163]
	s_nop 0
	v_fma_f32 v4, v2, s15, -v6
	v_fmac_f32_e32 v4, 0xb102e308, v2
	v_pk_add_f32 v[2:3], v[6:7], v[4:5]
	s_nop 0
	v_sub_f32_e32 v5, v3, v5
	v_sub_f32_e32 v5, v7, v5
	v_add_f32_e32 v9, v8, v5
	v_mov_b32_e32 v8, v6
	v_pk_add_f32 v[6:7], v[2:3], v[6:7] neg_lo:[0,1] neg_hi:[0,1]
	v_pk_add_f32 v[10:11], v[2:3], v[8:9]
	v_mov_b32_e32 v5, v2
	v_mov_b32_e32 v7, v11
	v_pk_add_f32 v[12:13], v[4:5], v[6:7] neg_lo:[0,1] neg_hi:[0,1]
	v_pk_add_f32 v[4:5], v[4:5], v[6:7]
	v_mov_b32_e32 v16, v3
	v_pk_add_f32 v[6:7], v[4:5], v[2:3] op_sel:[1,0] op_sel_hi:[0,1] neg_lo:[0,1] neg_hi:[0,1]
	v_pk_add_f32 v[14:15], v[10:11], v[6:7] op_sel_hi:[1,0] neg_lo:[0,1] neg_hi:[0,1]
	v_mov_b32_e32 v10, v11
	v_mov_b32_e32 v11, v5
	v_mov_b32_e32 v17, v6
	v_pk_add_f32 v[6:7], v[10:11], v[16:17] neg_lo:[0,1] neg_hi:[0,1]
	v_mov_b32_e32 v8, v9
	v_mov_b32_e32 v9, v2
	v_pk_add_f32 v[2:3], v[8:9], v[6:7] neg_lo:[0,1] neg_hi:[0,1]
	v_mov_b32_e32 v14, v12
	v_pk_add_f32 v[6:7], v[14:15], v[2:3]
	v_mov_b32_e32 v13, v5
	v_pk_add_f32 v[8:9], v[6:7], v[6:7] op_sel:[0,1] op_sel_hi:[1,0]
	s_nop 0
	v_pk_add_f32 v[4:5], v[4:5], v[8:9] op_sel:[1,0] op_sel_hi:[0,1]
	v_mov_b32_e32 v7, v4
	v_pk_add_f32 v[10:11], v[6:7], v[12:13] neg_lo:[0,1] neg_hi:[0,1]
	v_mov_b32_e32 v3, v8
	v_sub_f32_e32 v5, v6, v10
	v_pk_add_f32 v[2:3], v[2:3], v[10:11] neg_lo:[0,1] neg_hi:[0,1]
	v_sub_f32_e32 v5, v12, v5
	v_add_f32_e32 v2, v2, v5
	v_add_f32_e32 v2, v2, v3
	v_add_f32_e32 v2, v4, v2
	v_cndmask_b32_e32 v2, v222, v2, vcc
	v_cmp_lt_f32_e64 vcc, |v19|, s22
	s_nop 1
	v_cndmask_b32_e32 v2, v2, v19, vcc
	v_mul_f32_e32 v19, 0xbfb8aa3b, v2
	global_load_dword v2, v18, s[6:7]
	s_waitcnt vmcnt(0)
; __device__ __forceinline__ float log2_gamma(float logit) { return -log1pf(expf(-logit)) * 1.4426950408889634f; }
; __device__ __forceinline__ void r1s_sweep(const bf16_t* __restrict__ kT, const bf16_t* __restrict__ vT, bf16_t* __restrict__ STd, int bh, int s, int wid, int fr, int fq, float lg, float gC, bool fwd) {
;     float w[4][8];
; #pragma unroll
;     for (int ks = 0; ks < 4; ++ks)
; #pragma unroll
;         for (int e = 0; e < 8; ++e) { const int t = 32 * ks + 8 * fq + e; w[ks][e] = __builtin_amdgcn_exp2f(lg * (float)(fwd ? 127 - t : t)); }
;     f32x4 S = {0.f, 0.f, 0.f, 0.f};
;     const size_t koff = (size_t)(16 * s + fr) * 128 + 8 * fq, voff = (size_t)(16 * wid + fr) * 128 + 8 * fq;
;     bf16_t* dst0 = STd + (16 * wid + fr) * 128 + 16 * s + 4 * fq;
;     ...
;     bf16x8 kA[4], vA[4], kB[4], vB[4];
;     r1s_load(kT, vT, bh, R1S_CC(0), koff, voff, kA, vA);
; __device__ __forceinline__ void r1s_phase(KP p, int G, int bid, int wv) {
;     ...
;         const int bh = u >> 3, s = u & 7, h = bh & 7;
;         float lf = log2_gamma(p->in[18][h]), lb = log2_gamma(p->in[19][h]);
;         asm volatile("" : "+v"(lf), "+v"(lb));
;         r1s_sweep(kT, vT, ST + (size_t)(bh * 2 + 0) * 16 * 16384, bh, s, wid, fr, fq, lf, __builtin_amdgcn_exp2f(128.0f * lf), true);
;         r1s_sweep(kT, vT, ST + (size_t)(bh * 2 + 1) * 16 * 16384, bh, s, wid, fr, fq, lb, __builtin_amdgcn_exp2f(128.0f * lb), false);
	v_mul_f32_e32 v3, 0xbfb8aa3b, v2
	v_fma_f32 v4, v2, s12, -v3
	v_rndne_f32_e32 v5, v3
	v_fmac_f32_e32 v4, 0xb2a5705f, v2
	v_sub_f32_e32 v3, v3, v5
	v_add_f32_e32 v3, v3, v4
	v_exp_f32_e32 v3, v3
	v_cvt_i32_f32_e32 v4, v5
	v_cmp_nlt_f32_e32 vcc, s93, v2
	v_ldexp_f32 v3, v3, v4
	s_nop 0
	v_cndmask_b32_e32 v3, 0, v3, vcc
	v_cmp_ngt_f32_e32 vcc, s13, v2
	s_nop 1
	v_cndmask_b32_e32 v18, v222, v3, vcc
	v_add_f32_e32 v4, 1.0, v18
	v_add_f32_e32 v2, -1.0, v4
	v_sub_f32_e32 v3, v2, v4
	v_add_f32_e32 v3, 1.0, v3
	v_sub_f32_e32 v2, v18, v2
	v_add_f32_e32 v5, v2, v3
	v_frexp_mant_f32_e32 v2, v4
	v_cmp_gt_f32_e32 vcc, s35, v2
	v_cvt_f64_f32_e32 v[2:3], v4
	v_frexp_exp_i32_f64_e32 v2, v[2:3]
	v_subbrev_co_u32_e32 v10, vcc, 0, v2, vcc
	v_sub_u32_e32 v2, 0, v10
	v_ldexp_f32 v3, v4, v2
	v_add_f32_e32 v4, -1.0, v3
	v_add_f32_e32 v6, 1.0, v3
	v_ldexp_f32 v2, v5, v2
	v_add_f32_e32 v5, 1.0, v4
	v_add_f32_e32 v7, -1.0, v6
	v_sub_f32_e32 v5, v3, v5
	v_sub_f32_e32 v3, v3, v7
	v_add_f32_e32 v5, v2, v5
	v_add_f32_e32 v2, v2, v3
	v_add_f32_e32 v11, v6, v2
	v_rcp_f32_e32 v13, v11
	v_sub_f32_e32 v3, v6, v11
	v_add_f32_e32 v12, v2, v3
	v_add_f32_e32 v3, v4, v5
	v_mul_f32_e32 v15, v3, v13
	v_sub_f32_e32 v2, v4, v3
	v_mul_f32_e32 v4, v11, v15
	v_fma_f32 v6, v15, v11, -v4
	v_fmac_f32_e32 v6, v15, v12
	v_add_f32_e32 v14, v5, v2
	v_add_f32_e32 v2, v4, v6
	v_sub_f32_e32 v5, v3, v2
	v_pk_add_f32 v[8:9], v[2:3], v[4:5] neg_lo:[0,1] neg_hi:[0,1]
	v_mov_b32_e32 v7, v2
	v_pk_add_f32 v[2:3], v[8:9], v[6:7] neg_lo:[0,1] neg_hi:[0,1]
	v_cmp_neq_f32_e32 vcc, s14, v18
	v_add_f32_e32 v3, v14, v3
	v_add_f32_e32 v2, v2, v3
	v_add_f32_e32 v3, v5, v2
	v_mul_f32_e32 v14, v13, v3
	v_mul_f32_e32 v4, v11, v14
	v_fma_f32 v6, v14, v11, -v4
	v_fmac_f32_e32 v6, v14, v12
	v_sub_f32_e32 v5, v5, v3
	v_add_f32_e32 v11, v2, v5
	v_add_f32_e32 v2, v4, v6
	v_sub_f32_e32 v5, v3, v2
	v_pk_add_f32 v[8:9], v[2:3], v[4:5] neg_lo:[0,1] neg_hi:[0,1]
	v_mov_b32_e32 v7, v2
	v_pk_add_f32 v[2:3], v[8:9], v[6:7] neg_lo:[0,1] neg_hi:[0,1]
	s_nop 0
	v_add_f32_e32 v3, v11, v3
	v_add_f32_e32 v2, v2, v3
	v_add_f32_e32 v3, v15, v14
	v_add_f32_e32 v2, v5, v2
	v_sub_f32_e32 v4, v3, v15
	v_mul_f32_e32 v2, v13, v2
	v_sub_f32_e32 v4, v14, v4
	v_add_f32_e32 v4, v4, v2
	v_add_f32_e32 v6, v3, v4
	v_mul_f32_e32 v7, v6, v6
	v_fmamk_f32 v2, v7, 0x3e9b6dac, v246
	v_fmaak_f32 v163, v7, v2, 0x3f2aaada
	v_cvt_f32_i32_e32 v2, v10
	v_sub_f32_e32 v3, v6, v3
	v_sub_f32_e32 v3, v4, v3
	v_ldexp_f32 v8, v3, 1
	v_mul_f32_e32 v3, v6, v7
	v_ldexp_f32 v5, v6, 1
	v_pk_mul_f32 v[6:7], v[2:3], v[162:163]
	s_nop 0
	v_fma_f32 v4, v2, s15, -v6
	v_fmac_f32_e32 v4, 0xb102e308, v2
	v_pk_add_f32 v[2:3], v[6:7], v[4:5]
	s_nop 0
	v_sub_f32_e32 v5, v3, v5
	v_sub_f32_e32 v5, v7, v5
	v_add_f32_e32 v9, v8, v5
	v_mov_b32_e32 v8, v6
	v_pk_add_f32 v[6:7], v[2:3], v[6:7] neg_lo:[0,1] neg_hi:[0,1]
	v_pk_add_f32 v[10:11], v[2:3], v[8:9]
	v_mov_b32_e32 v5, v2
	v_mov_b32_e32 v7, v11
	v_pk_add_f32 v[12:13], v[4:5], v[6:7] neg_lo:[0,1] neg_hi:[0,1]
	v_pk_add_f32 v[4:5], v[4:5], v[6:7]
	v_mov_b32_e32 v16, v3
	v_pk_add_f32 v[6:7], v[4:5], v[2:3] op_sel:[1,0] op_sel_hi:[0,1] neg_lo:[0,1] neg_hi:[0,1]
	v_pk_add_f32 v[14:15], v[10:11], v[6:7] op_sel_hi:[1,0] neg_lo:[0,1] neg_hi:[0,1]
	v_mov_b32_e32 v10, v11
	v_mov_b32_e32 v11, v5
	v_mov_b32_e32 v17, v6
	v_pk_add_f32 v[6:7], v[10:11], v[16:17] neg_lo:[0,1] neg_hi:[0,1]
	v_mov_b32_e32 v8, v9
	v_mov_b32_e32 v9, v2
	v_pk_add_f32 v[2:3], v[8:9], v[6:7] neg_lo:[0,1] neg_hi:[0,1]
	v_mov_b32_e32 v14, v12
	v_pk_add_f32 v[6:7], v[14:15], v[2:3]
	v_mov_b32_e32 v13, v5
	v_pk_add_f32 v[8:9], v[6:7], v[6:7] op_sel:[0,1] op_sel_hi:[1,0]
	s_nop 0
	v_pk_add_f32 v[4:5], v[4:5], v[8:9] op_sel:[1,0] op_sel_hi:[0,1]
	v_mov_b32_e32 v7, v4
	v_pk_add_f32 v[10:11], v[6:7], v[12:13] neg_lo:[0,1] neg_hi:[0,1]
	v_mov_b32_e32 v3, v8
	v_sub_f32_e32 v5, v6, v10
	v_pk_add_f32 v[2:3], v[2:3], v[10:11] neg_lo:[0,1] neg_hi:[0,1]
	v_sub_f32_e32 v5, v12, v5
	v_add_f32_e32 v2, v2, v5
	v_add_f32_e32 v2, v2, v3
	v_add_f32_e32 v2, v4, v2
	v_cndmask_b32_e32 v2, v222, v2, vcc
	v_cmp_lt_f32_e64 vcc, |v18|, s22
	s_nop 1
	v_cndmask_b32_e32 v2, v2, v18, vcc
	v_mul_f32_e32 v163, 0xbfb8aa3b, v2
	v_and_b32_e32 v164, 15, v221
	v_bfe_u32 v165, v221, 4, 2
	v_lshrrev_b32_e32 v166, 6, v221
	v_lshlrev_b32_e32 v167, 3, v165
	s_and_b32 s8, s1, 7
	s_lshl_b32 s8, s8, 4
	v_add_u32_e32 v168, s8, v164
	v_lshlrev_b32_e32 v168, 8, v168
	v_lshl_add_u32 v170, v165, 4, v168
	v_lshl_add_u32 v168, v166, 4, v164
	v_lshlrev_b32_e32 v169, 8, v168
	v_lshl_add_u32 v171, v165, 4, v169
	v_lshl_add_u32 v172, v165, 3, v169
	s_lshl_b32 s9, s8, 1
	v_add_u32_e32 v172, s9, v172
	s_ashr_i32 s10, s1, 3
	s_mul_i32 s11, s10, 0x90000
	s_add_u32 s16, s2, s11
	s_addc_u32 s17, s3, 0
	s_add_u32 s18, s16, 0x1200000
	s_addc_u32 s19, s17, 0
	s_mov_b32 s23, 0
; __device__ __forceinline__ void r1s_sweep(const bf16_t* __restrict__ kT, const bf16_t* __restrict__ vT, bf16_t* __restrict__ STd, int bh, int s, int wid, int fr, int fq, float lg, float gC, bool fwd) {
;     float w[4][8];
; #pragma unroll
;     for (int ks = 0; ks < 4; ++ks)
; #pragma unroll
;         for (int e = 0; e < 8; ++e) { const int t = 32 * ks + 8 * fq + e; w[ks][e] = __builtin_amdgcn_exp2f(lg * (float)(fwd ? 127 - t : t)); }
;     f32x4 S = {0.f, 0.f, 0.f, 0.f};
;     const size_t koff = (size_t)(16 * s + fr) * 128 + 8 * fq, voff = (size_t)(16 * wid + fr) * 128 + 8 * fq;
;     bf16_t* dst0 = STd + (16 * wid + fr) * 128 + 16 * s + 4 * fq;
;     ...
;     bf16x8 kA[4], vA[4], kB[4], vB[4];
;     r1s_load(kT, vT, bh, R1S_CC(0), koff, voff, kA, vA);
.Lr1_dir:
	s_cmp_eq_u32 s23, 0
	s_cselect_b64 s[98:99], 0, -1
	s_cselect_b32 s28, 0x7f, 0
	s_nop 1
	v_cndmask_b32_e64 v54, v19, v163, s[98:99]
	s_ashr_i32 s20, s1, 3
	s_lshl_b32 s20, s20, 20
	s_lshl_b32 s25, s23, 19
	s_add_u32 s20, s20, s25
	s_add_u32 s20, s20, 0xac00000
	s_add_u32 s20, s2, s20
	s_addc_u32 s21, s3, 0
	s_lshl_b32 s26, s23, 15
	s_add_u32 s8, s16, s26
	s_addc_u32 s9, s17, 0
	s_add_u32 s10, s18, s26
	s_addc_u32 s11, s19, 0
	global_load_dwordx4 v[2:5], v170, s[8:9]
	global_load_dwordx4 v[6:9], v170, s[8:9] offset:64
	global_load_dwordx4 v[10:13], v170, s[8:9] offset:128
	global_load_dwordx4 v[14:17], v170, s[8:9] offset:192
	global_load_dwordx4 v[70:73], v171, s[10:11]
	global_load_dwordx4 v[74:77], v171, s[10:11] offset:64
	global_load_dwordx4 v[78:81], v171, s[10:11] offset:128
	global_load_dwordx4 v[82:85], v171, s[10:11] offset:192
	v_add_u32_e32 v168, 0, v167
	v_xor_b32_e32 v168, s28, v168
	v_cvt_f32_u32_e32 v168, v168
	v_mul_f32_e32 v168, v54, v168
	v_exp_f32_e32 v224, v168
	v_add_u32_e32 v168, 1, v167
	v_xor_b32_e32 v168, s28, v168
	v_cvt_f32_u32_e32 v168, v168
	v_mul_f32_e32 v168, v54, v168
	v_exp_f32_e32 v225, v168
	v_add_u32_e32 v168, 2, v167
	v_xor_b32_e32 v168, s28, v168
	v_cvt_f32_u32_e32 v168, v168
	v_mul_f32_e32 v168, v54, v168
	v_exp_f32_e32 v226, v168
	v_add_u32_e32 v168, 3, v167
	v_xor_b32_e32 v168, s28, v168
	v_cvt_f32_u32_e32 v168, v168
	v_mul_f32_e32 v168, v54, v168
	v_exp_f32_e32 v227, v168
	v_add_u32_e32 v168, 4, v167
	v_xor_b32_e32 v168, s28, v168
	v_cvt_f32_u32_e32 v168, v168
	v_mul_f32_e32 v168, v54, v168
	v_exp_f32_e32 v228, v168
	v_add_u32_e32 v168, 5, v167
	v_xor_b32_e32 v168, s28, v168
	v_cvt_f32_u32_e32 v168, v168
	v_mul_f32_e32 v168, v54, v168
	v_exp_f32_e32 v229, v168
	v_add_u32_e32 v168, 6, v167
	v_xor_b32_e32 v168, s28, v168
	v_cvt_f32_u32_e32 v168, v168
	v_mul_f32_e32 v168, v54, v168
	v_exp_f32_e32 v230, v168
	v_add_u32_e32 v168, 7, v167
	v_xor_b32_e32 v168, s28, v168
	v_cvt_f32_u32_e32 v168, v168
	v_mul_f32_e32 v168, v54, v168
	v_exp_f32_e32 v231, v168
	v_add_u32_e32 v168, 32, v167
	v_xor_b32_e32 v168, s28, v168
	v_cvt_f32_u32_e32 v168, v168
	v_mul_f32_e32 v168, v54, v168
	v_exp_f32_e32 v232, v168
	v_add_u32_e32 v168, 33, v167
	v_xor_b32_e32 v168, s28, v168
	v_cvt_f32_u32_e32 v168, v168
	v_mul_f32_e32 v168, v54, v168
	v_exp_f32_e32 v233, v168
	v_add_u32_e32 v168, 34, v167
	v_xor_b32_e32 v168, s28, v168
	v_cvt_f32_u32_e32 v168, v168
	v_mul_f32_e32 v168, v54, v168
	v_exp_f32_e32 v234, v168
	v_add_u32_e32 v168, 35, v167
	v_xor_b32_e32 v168, s28, v168
	v_cvt_f32_u32_e32 v168, v168
	v_mul_f32_e32 v168, v54, v168
	v_exp_f32_e32 v235, v168
	v_add_u32_e32 v168, 36, v167
	v_xor_b32_e32 v168, s28, v168
	v_cvt_f32_u32_e32 v168, v168
	v_mul_f32_e32 v168, v54, v168
	v_exp_f32_e32 v236, v168
	v_add_u32_e32 v168, 37, v167
	v_xor_b32_e32 v168, s28, v168
	v_cvt_f32_u32_e32 v168, v168
	v_mul_f32_e32 v168, v54, v168
	v_exp_f32_e32 v237, v168
	v_add_u32_e32 v168, 38, v167
	v_xor_b32_e32 v168, s28, v168
	v_cvt_f32_u32_e32 v168, v168
	v_mul_f32_e32 v168, v54, v168
	v_exp_f32_e32 v238, v168
	v_add_u32_e32 v168, 39, v167
	v_xor_b32_e32 v168, s28, v168
	v_cvt_f32_u32_e32 v168, v168
	v_mul_f32_e32 v168, v54, v168
	v_exp_f32_e32 v239, v168
	v_add_u32_e32 v168, 64, v167
	v_xor_b32_e32 v168, s28, v168
	v_cvt_f32_u32_e32 v168, v168
	v_mul_f32_e32 v168, v54, v168
	v_exp_f32_e32 v240, v168
	v_add_u32_e32 v168, 65, v167
	v_xor_b32_e32 v168, s28, v168
	v_cvt_f32_u32_e32 v168, v168
	v_mul_f32_e32 v168, v54, v168
	v_exp_f32_e32 v241, v168
	v_add_u32_e32 v168, 66, v167
	v_xor_b32_e32 v168, s28, v168
	v_cvt_f32_u32_e32 v168, v168
	v_mul_f32_e32 v168, v54, v168
	v_exp_f32_e32 v242, v168
	v_add_u32_e32 v168, 67, v167
	v_xor_b32_e32 v168, s28, v168
	v_cvt_f32_u32_e32 v168, v168
	v_mul_f32_e32 v168, v54, v168
	v_exp_f32_e32 v243, v168
	v_add_u32_e32 v168, 68, v167
	v_xor_b32_e32 v168, s28, v168
	v_cvt_f32_u32_e32 v168, v168
	v_mul_f32_e32 v168, v54, v168
	v_exp_f32_e32 v244, v168
	v_add_u32_e32 v168, 69, v167
	v_xor_b32_e32 v168, s28, v168
	v_cvt_f32_u32_e32 v168, v168
	v_mul_f32_e32 v168, v54, v168
	v_exp_f32_e32 v245, v168
	v_add_u32_e32 v168, 70, v167
	v_xor_b32_e32 v168, s28, v168
	v_cvt_f32_u32_e32 v168, v168
	v_mul_f32_e32 v168, v54, v168
	v_exp_f32_e32 v246, v168
	v_add_u32_e32 v168, 71, v167
	v_xor_b32_e32 v168, s28, v168
	v_cvt_f32_u32_e32 v168, v168
	v_mul_f32_e32 v168, v54, v168
	v_exp_f32_e32 v247, v168
	v_add_u32_e32 v168, 96, v167
	v_xor_b32_e32 v168, s28, v168
	v_cvt_f32_u32_e32 v168, v168
	v_mul_f32_e32 v168, v54, v168
	v_exp_f32_e32 v248, v168
	v_add_u32_e32 v168, 97, v167
	v_xor_b32_e32 v168, s28, v168
	v_cvt_f32_u32_e32 v168, v168
	v_mul_f32_e32 v168, v54, v168
	v_exp_f32_e32 v249, v168
	v_add_u32_e32 v168, 98, v167
	v_xor_b32_e32 v168, s28, v168
	v_cvt_f32_u32_e32 v168, v168
	v_mul_f32_e32 v168, v54, v168
	v_exp_f32_e32 v250, v168
	v_add_u32_e32 v168, 99, v167
	v_xor_b32_e32 v168, s28, v168
	v_cvt_f32_u32_e32 v168, v168
	v_mul_f32_e32 v168, v54, v168
	v_exp_f32_e32 v251, v168
	v_add_u32_e32 v168, 100, v167
	v_xor_b32_e32 v168, s28, v168
	v_cvt_f32_u32_e32 v168, v168
	v_mul_f32_e32 v168, v54, v168
	v_exp_f32_e32 v210, v168
	v_add_u32_e32 v168, 101, v167
	v_xor_b32_e32 v168, s28, v168
	v_cvt_f32_u32_e32 v168, v168
	v_mul_f32_e32 v168, v54, v168
	v_exp_f32_e32 v211, v168
	v_add_u32_e32 v168, 102, v167
	v_xor_b32_e32 v168, s28, v168
	v_cvt_f32_u32_e32 v168, v168
	v_mul_f32_e32 v168, v54, v168
	v_exp_f32_e32 v212, v168
	v_add_u32_e32 v168, 103, v167
	v_xor_b32_e32 v168, s28, v168
	v_cvt_f32_u32_e32 v168, v168
	v_mul_f32_e32 v168, v54, v168
	v_exp_f32_e32 v213, v168
	v_mul_f32_e32 v168, 0x43000000, v54
	v_exp_f32_e32 v90, v168
	v_mov_b32_e32 v36, 0
	v_mov_b32_e32 v37, 0
	v_mov_b32_e32 v38, 0
	v_mov_b32_e32 v39, 0
	s_mov_b32 s24, 0
; __device__ __forceinline__ unsigned cvt_pk_bf16(float lo, float hi) { unsigned r; asm("v_cvt_pk_bf16_f32 %0, %1, %2" : "=v"(r) : "v"(lo), "v"(hi)); return r; }
; __device__ __forceinline__ float bf2f(unsigned b) { return __uint_as_float(b << 16); }
; __device__ __forceinline__ void r1s_step(const bf16x8 (&kk)[4], const bf16x8 (&vv)[4], const float (&w)[4][8], f32x4& S, float gC, bool st, bf16_t* dst) {
;     f32x4 acc = {0.f, 0.f, 0.f, 0.f};
; #pragma unroll
;     for (int ks = 0; ks < 4; ++ks) {
;         float f[8];
; #pragma unroll
;         for (int e = 0; e < 8; ++e) f[e] = bf2f((unsigned)(unsigned short)kk[ks][e]) * w[ks][e];
;         u32x4 wf; wf.x = cvt_pk_bf16(f[0], f[1]); wf.y = cvt_pk_bf16(f[2], f[3]); wf.z = cvt_pk_bf16(f[4], f[5]); wf.w = cvt_pk_bf16(f[6], f[7]);
;         acc = __builtin_amdgcn_mfma_f32_16x16x32_bf16(__builtin_bit_cast(bf16x8, wf), vv[ks], acc, 0, 0, 0);
;     }
;     if (st) { u32x2 o; o.x = cvt_pk_bf16(S[0], S[1]); o.y = cvt_pk_bf16(S[2], S[3]); *(u32x2*)dst = o; }
;     S = S * gC + acc;
; __device__ __forceinline__ void r1s_sweep(const bf16_t* __restrict__ kT, const bf16_t* __restrict__ vT, bf16_t* __restrict__ STd, int bh, int s, int wid, int fr, int fq, float lg, float gC, bool fwd) {
;     ...
; #pragma unroll
;     for (int i = 0; i < 18; i += 2) {
;         r1s_load(kT, vT, bh, R1S_CC(i + 1), koff, voff, kB, vB);
;         { const int cc = R1S_CC(i); r1s_step(kA, vA, w, S, gC, cc >= 2, dst0 + (size_t)(cc >= 2 ? cc - 2 : 0) * 16384); }
;         if (i + 2 < 18) r1s_load(kT, vT, bh, R1S_CC(i + 2), koff, voff, kA, vA);
;         { const int cc = R1S_CC(i + 1); r1s_step(kB, vB, w, S, gC, cc >= 2, dst0 + (size_t)(cc >= 2 ? cc - 2 : 0) * 16384); }
.Lr1_step:
	s_add_i32 s25, s24, 1
	s_sub_i32 s26, 19, s25
	s_sub_i32 s27, 1, s25
	s_cmp_lt_u32 s25, 2
	s_cselect_b32 s26, s27, s26
	s_cmp_eq_u32 s23, 0
	s_cselect_b32 s26, s25, s26
	s_min_u32 s26, s26, 17
	s_lshl_b32 s26, s26, 15
	s_add_u32 s8, s16, s26
	s_addc_u32 s9, s17, 0
	s_add_u32 s10, s18, s26
	s_addc_u32 s11, s19, 0
	global_load_dwordx4 v[20:23], v170, s[8:9]
	global_load_dwordx4 v[24:27], v170, s[8:9] offset:64
	global_load_dwordx4 v[28:31], v170, s[8:9] offset:128
	global_load_dwordx4 v[32:35], v170, s[8:9] offset:192
	global_load_dwordx4 v[94:97], v171, s[10:11]
	global_load_dwordx4 v[98:101], v171, s[10:11] offset:64
	global_load_dwordx4 v[102:105], v171, s[10:11] offset:128
	global_load_dwordx4 v[106:109], v171, s[10:11] offset:192
	s_waitcnt vmcnt(8)
	v_lshlrev_b32_e32 v44, 16, v2
	v_lshlrev_b32_e32 v45, 16, v3
	v_lshlrev_b32_e32 v46, 16, v4
	v_lshlrev_b32_e32 v47, 16, v5
	v_and_b32_e32 v2, 0xffff0000, v2
	v_and_b32_e32 v3, 0xffff0000, v3
	v_and_b32_e32 v4, 0xffff0000, v4
	v_and_b32_e32 v5, 0xffff0000, v5
	v_mul_f32_e32 v44, v224, v44
	v_mul_f32_e32 v45, v226, v45
	v_mul_f32_e32 v46, v228, v46
	v_mul_f32_e32 v47, v230, v47
	v_mul_f32_e32 v2, v225, v2
	v_mul_f32_e32 v3, v227, v3
	v_mul_f32_e32 v4, v229, v4
	v_mul_f32_e32 v5, v231, v5
	v_cvt_pk_bf16_f32 v44, v44, v2
	v_cvt_pk_bf16_f32 v45, v45, v3
	v_cvt_pk_bf16_f32 v46, v46, v4
	v_cvt_pk_bf16_f32 v47, v47, v5
	v_lshlrev_b32_e32 v86, 16, v6
	v_lshlrev_b32_e32 v87, 16, v7
	v_lshlrev_b32_e32 v88, 16, v8
	v_lshlrev_b32_e32 v89, 16, v9
	v_and_b32_e32 v6, 0xffff0000, v6
	v_and_b32_e32 v7, 0xffff0000, v7
	v_and_b32_e32 v8, 0xffff0000, v8
	v_and_b32_e32 v9, 0xffff0000, v9
	v_mul_f32_e32 v86, v232, v86
	v_mul_f32_e32 v87, v234, v87
	v_mul_f32_e32 v88, v236, v88
	v_mul_f32_e32 v89, v238, v89
	v_mul_f32_e32 v6, v233, v6
	v_mul_f32_e32 v7, v235, v7
	v_mul_f32_e32 v8, v237, v8
	v_mul_f32_e32 v9, v239, v9
	v_cvt_pk_bf16_f32 v86, v86, v6
	v_cvt_pk_bf16_f32 v87, v87, v7
	v_cvt_pk_bf16_f32 v88, v88, v8
	v_cvt_pk_bf16_f32 v89, v89, v9
	s_nop 0
	v_mfma_f32_16x16x32_bf16 v[40:43], v[44:47], v[70:73], 0
	v_lshlrev_b32_e32 v44, 16, v10
	v_lshlrev_b32_e32 v45, 16, v11
	v_lshlrev_b32_e32 v46, 16, v12
	v_lshlrev_b32_e32 v47, 16, v13
	v_and_b32_e32 v10, 0xffff0000, v10
	v_and_b32_e32 v11, 0xffff0000, v11
	v_and_b32_e32 v12, 0xffff0000, v12
	v_and_b32_e32 v13, 0xffff0000, v13
	v_mul_f32_e32 v44, v240, v44
	v_mul_f32_e32 v45, v242, v45
	v_mul_f32_e32 v46, v244, v46
	v_mul_f32_e32 v47, v246, v47
	v_mul_f32_e32 v10, v241, v10
	v_mul_f32_e32 v11, v243, v11
	v_mul_f32_e32 v12, v245, v12
	v_mul_f32_e32 v13, v247, v13
	v_cvt_pk_bf16_f32 v44, v44, v10
	v_cvt_pk_bf16_f32 v45, v45, v11
	v_cvt_pk_bf16_f32 v46, v46, v12
	v_cvt_pk_bf16_f32 v47, v47, v13
	v_mfma_f32_16x16x32_bf16 v[40:43], v[86:89], v[74:77], v[40:43]
	v_lshlrev_b32_e32 v86, 16, v14
	v_lshlrev_b32_e32 v87, 16, v15
	v_lshlrev_b32_e32 v88, 16, v16
	v_lshlrev_b32_e32 v89, 16, v17
	v_and_b32_e32 v14, 0xffff0000, v14
	v_and_b32_e32 v15, 0xffff0000, v15
	v_and_b32_e32 v16, 0xffff0000, v16
	v_and_b32_e32 v17, 0xffff0000, v17
	v_mul_f32_e32 v86, v248, v86
	v_mul_f32_e32 v87, v250, v87
	v_mul_f32_e32 v88, v210, v88
	v_mul_f32_e32 v89, v212, v89
	v_mul_f32_e32 v14, v249, v14
	v_mul_f32_e32 v15, v251, v15
	v_mul_f32_e32 v16, v211, v16
	v_mul_f32_e32 v17, v213, v17
	v_cvt_pk_bf16_f32 v86, v86, v14
	v_cvt_pk_bf16_f32 v87, v87, v15
	v_cvt_pk_bf16_f32 v88, v88, v16
	v_cvt_pk_bf16_f32 v89, v89, v17
	v_mfma_f32_16x16x32_bf16 v[40:43], v[44:47], v[78:81], v[40:43]
	s_nop 1
	v_mfma_f32_16x16x32_bf16 v[40:43], v[86:89], v[82:85], v[40:43]
	s_add_i32 s25, s24, 0
	s_cmp_lt_u32 s25, 2
	s_cbranch_scc1 .Lr1_nost_0
	s_sub_i32 s26, 17, s25
	s_sub_i32 s27, s25, 2
	s_cmp_eq_u32 s23, 0
	s_cselect_b32 s26, s27, s26
	s_lshl_b32 s26, s26, 15
	s_add_u32 s8, s20, s26
	s_addc_u32 s9, s21, 0
	v_cvt_pk_bf16_f32 v48, v36, v37
	v_cvt_pk_bf16_f32 v49, v38, v39
	global_store_dwordx2 v172, v[48:49], s[8:9]
; __device__ __forceinline__ unsigned cvt_pk_bf16(float lo, float hi) { unsigned r; asm("v_cvt_pk_bf16_f32 %0, %1, %2" : "=v"(r) : "v"(lo), "v"(hi)); return r; }
; __device__ __forceinline__ float bf2f(unsigned b) { return __uint_as_float(b << 16); }
; __device__ __forceinline__ void r1s_step(const bf16x8 (&kk)[4], const bf16x8 (&vv)[4], const float (&w)[4][8], f32x4& S, float gC, bool st, bf16_t* dst) {
;     f32x4 acc = {0.f, 0.f, 0.f, 0.f};
; #pragma unroll
;     for (int ks = 0; ks < 4; ++ks) {
;         float f[8];
; #pragma unroll
;         for (int e = 0; e < 8; ++e) f[e] = bf2f((unsigned)(unsigned short)kk[ks][e]) * w[ks][e];
;         u32x4 wf; wf.x = cvt_pk_bf16(f[0], f[1]); wf.y = cvt_pk_bf16(f[2], f[3]); wf.z = cvt_pk_bf16(f[4], f[5]); wf.w = cvt_pk_bf16(f[6], f[7]);
;         acc = __builtin_amdgcn_mfma_f32_16x16x32_bf16(__builtin_bit_cast(bf16x8, wf), vv[ks], acc, 0, 0, 0);
;     }
;     if (st) { u32x2 o; o.x = cvt_pk_bf16(S[0], S[1]); o.y = cvt_pk_bf16(S[2], S[3]); *(u32x2*)dst = o; }
;     S = S * gC + acc;
; }
; __device__ __forceinline__ void r1s_sweep(const bf16_t* __restrict__ kT, const bf16_t* __restrict__ vT, bf16_t* __restrict__ STd, int bh, int s, int wid, int fr, int fq, float lg, float gC, bool fwd) {
;     ...
; #pragma unroll
;     for (int i = 0; i < 18; i += 2) {
;         r1s_load(kT, vT, bh, R1S_CC(i + 1), koff, voff, kB, vB);
;         { const int cc = R1S_CC(i); r1s_step(kA, vA, w, S, gC, cc >= 2, dst0 + (size_t)(cc >= 2 ? cc - 2 : 0) * 16384); }
;         if (i + 2 < 18) r1s_load(kT, vT, bh, R1S_CC(i + 2), koff, voff, kA, vA);
;         { const int cc = R1S_CC(i + 1); r1s_step(kB, vB, w, S, gC, cc >= 2, dst0 + (size_t)(cc >= 2 ? cc - 2 : 0) * 16384); }
;     }
.Lr1_nost_0:
	s_nop 7
	v_pk_fma_f32 v[36:37], v[90:91], v[36:37], v[40:41] op_sel_hi:[0,1,1]
	v_pk_fma_f32 v[38:39], v[90:91], v[38:39], v[42:43] op_sel_hi:[0,1,1]
	s_add_i32 s25, s24, 2
	s_sub_i32 s26, 19, s25
	s_sub_i32 s27, 1, s25
	s_cmp_lt_u32 s25, 2
	s_cselect_b32 s26, s27, s26
	s_cmp_eq_u32 s23, 0
	s_cselect_b32 s26, s25, s26
	s_min_u32 s26, s26, 17
	s_lshl_b32 s26, s26, 15
	s_add_u32 s8, s16, s26
	s_addc_u32 s9, s17, 0
	s_add_u32 s10, s18, s26
	s_addc_u32 s11, s19, 0
	global_load_dwordx4 v[2:5], v170, s[8:9]
	global_load_dwordx4 v[6:9], v170, s[8:9] offset:64
	global_load_dwordx4 v[10:13], v170, s[8:9] offset:128
	global_load_dwordx4 v[14:17], v170, s[8:9] offset:192
	global_load_dwordx4 v[70:73], v171, s[10:11]
	global_load_dwordx4 v[74:77], v171, s[10:11] offset:64
	global_load_dwordx4 v[78:81], v171, s[10:11] offset:128
	global_load_dwordx4 v[82:85], v171, s[10:11] offset:192
	s_waitcnt vmcnt(8)
	v_lshlrev_b32_e32 v44, 16, v20
	v_lshlrev_b32_e32 v45, 16, v21
	v_lshlrev_b32_e32 v46, 16, v22
	v_lshlrev_b32_e32 v47, 16, v23
	v_and_b32_e32 v20, 0xffff0000, v20
	v_and_b32_e32 v21, 0xffff0000, v21
	v_and_b32_e32 v22, 0xffff0000, v22
	v_and_b32_e32 v23, 0xffff0000, v23
	v_mul_f32_e32 v44, v224, v44
	v_mul_f32_e32 v45, v226, v45
	v_mul_f32_e32 v46, v228, v46
	v_mul_f32_e32 v47, v230, v47
	v_mul_f32_e32 v20, v225, v20
	v_mul_f32_e32 v21, v227, v21
	v_mul_f32_e32 v22, v229, v22
	v_mul_f32_e32 v23, v231, v23
	v_cvt_pk_bf16_f32 v44, v44, v20
	v_cvt_pk_bf16_f32 v45, v45, v21
	v_cvt_pk_bf16_f32 v46, v46, v22
	v_cvt_pk_bf16_f32 v47, v47, v23
	v_lshlrev_b32_e32 v86, 16, v24
	v_lshlrev_b32_e32 v87, 16, v25
	v_lshlrev_b32_e32 v88, 16, v26
	v_lshlrev_b32_e32 v89, 16, v27
	v_and_b32_e32 v24, 0xffff0000, v24
	v_and_b32_e32 v25, 0xffff0000, v25
	v_and_b32_e32 v26, 0xffff0000, v26
	v_and_b32_e32 v27, 0xffff0000, v27
	v_mul_f32_e32 v86, v232, v86
	v_mul_f32_e32 v87, v234, v87
	v_mul_f32_e32 v88, v236, v88
	v_mul_f32_e32 v89, v238, v89
	v_mul_f32_e32 v24, v233, v24
	v_mul_f32_e32 v25, v235, v25
	v_mul_f32_e32 v26, v237, v26
	v_mul_f32_e32 v27, v239, v27
	v_cvt_pk_bf16_f32 v86, v86, v24
	v_cvt_pk_bf16_f32 v87, v87, v25
	v_cvt_pk_bf16_f32 v88, v88, v26
	v_cvt_pk_bf16_f32 v89, v89, v27
	s_nop 0
	v_mfma_f32_16x16x32_bf16 v[40:43], v[44:47], v[94:97], 0
	v_lshlrev_b32_e32 v44, 16, v28
	v_lshlrev_b32_e32 v45, 16, v29
	v_lshlrev_b32_e32 v46, 16, v30
	v_lshlrev_b32_e32 v47, 16, v31
	v_and_b32_e32 v28, 0xffff0000, v28
	v_and_b32_e32 v29, 0xffff0000, v29
	v_and_b32_e32 v30, 0xffff0000, v30
	v_and_b32_e32 v31, 0xffff0000, v31
	v_mul_f32_e32 v44, v240, v44
	v_mul_f32_e32 v45, v242, v45
	v_mul_f32_e32 v46, v244, v46
	v_mul_f32_e32 v47, v246, v47
	v_mul_f32_e32 v28, v241, v28
	v_mul_f32_e32 v29, v243, v29
	v_mul_f32_e32 v30, v245, v30
	v_mul_f32_e32 v31, v247, v31
	v_cvt_pk_bf16_f32 v44, v44, v28
	v_cvt_pk_bf16_f32 v45, v45, v29
	v_cvt_pk_bf16_f32 v46, v46, v30
	v_cvt_pk_bf16_f32 v47, v47, v31
	v_mfma_f32_16x16x32_bf16 v[40:43], v[86:89], v[98:101], v[40:43]
	v_lshlrev_b32_e32 v86, 16, v32
	v_lshlrev_b32_e32 v87, 16, v33
	v_lshlrev_b32_e32 v88, 16, v34
	v_lshlrev_b32_e32 v89, 16, v35
	v_and_b32_e32 v32, 0xffff0000, v32
	v_and_b32_e32 v33, 0xffff0000, v33
	v_and_b32_e32 v34, 0xffff0000, v34
	v_and_b32_e32 v35, 0xffff0000, v35
	v_mul_f32_e32 v86, v248, v86
	v_mul_f32_e32 v87, v250, v87
	v_mul_f32_e32 v88, v210, v88
	v_mul_f32_e32 v89, v212, v89
	v_mul_f32_e32 v32, v249, v32
	v_mul_f32_e32 v33, v251, v33
	v_mul_f32_e32 v34, v211, v34
	v_mul_f32_e32 v35, v213, v35
	v_cvt_pk_bf16_f32 v86, v86, v32
	v_cvt_pk_bf16_f32 v87, v87, v33
	v_cvt_pk_bf16_f32 v88, v88, v34
	v_cvt_pk_bf16_f32 v89, v89, v35
	v_mfma_f32_16x16x32_bf16 v[40:43], v[44:47], v[102:105], v[40:43]
	s_nop 1
	v_mfma_f32_16x16x32_bf16 v[40:43], v[86:89], v[106:109], v[40:43]
	s_add_i32 s25, s24, 1
	s_cmp_lt_u32 s25, 2
	s_cbranch_scc1 .Lr1_nost_1
	s_sub_i32 s26, 17, s25
	s_sub_i32 s27, s25, 2
	s_cmp_eq_u32 s23, 0
	s_cselect_b32 s26, s27, s26
	s_lshl_b32 s26, s26, 15
	s_add_u32 s8, s20, s26
	s_addc_u32 s9, s21, 0
	v_cvt_pk_bf16_f32 v48, v36, v37
	v_cvt_pk_bf16_f32 v49, v38, v39
	global_store_dwordx2 v172, v[48:49], s[8:9]
.Lr1_nost_1:
	s_nop 7
	v_pk_fma_f32 v[36:37], v[90:91], v[36:37], v[40:41] op_sel_hi:[0,1,1]
	v_pk_fma_f32 v[38:39], v[90:91], v[38:39], v[42:43] op_sel_hi:[0,1,1]
	s_add_i32 s24, s24, 2
	s_cmp_lt_u32 s24, 18
	s_cbranch_scc1 .Lr1_step
	s_add_i32 s23, s23, 1
	s_cmp_lt_u32 s23, 2
	s_cbranch_scc1 .Lr1_dir
	v_mov_b32_e32 v246, v219
	s_add_i32 s1, s1, s42
	s_add_i32 s0, s0, s97
	s_cmpk_gt_i32 s1, 0xff
	s_cbranch_scc0 .LBB0_113
